# scan output tile XOR-swizzled (4-way ds_write_b16 bank conflicts removed)
# speedup vs baseline: 1.0383x; 1.0128x over previous
; __device__ __forceinline__ float bflo(unsigned w) { return __uint_as_float(w << 16); }
; __device__ __forceinline__ float bfhi(unsigned w) { return __uint_as_float(w & 0xffff0000u); }
; __device__ __forceinline__ f32x4 mfma16(bf16x8 a, bf16x8 b, f32x4 c) { return __builtin_amdgcn_mfma_f32_16x16x32_bf16(a, b, c, 0, 0, 0); }
; __device__ __forceinline__ bf16x8 pack8(f32x4 a, f32x4 b) { v4u w; w.x = pk2(a[0], a[1]); w.y = pk2(a[2], a[3]); w.z = pk2(b[0], b[1]); w.w = pk2(b[2], b[3]); return __builtin_bit_cast(bf16x8, w); }
; __device__ __forceinline__ void scan_chain(const Params& P, bool smp, int s, int h, int sl, int lane) {
;     const int l15 = lane & 15, q4 = lane >> 4, e = 16 * sl + l15;
;     const int cu0 = smp ? 1024 + s : s * 128, nsteps = smp ? 1 : 128;
;     f32x4 S[4];
; #pragma unroll
;     for (int tau = 0; tau < 4; ++tau)
; #pragma unroll
;         for (int r = 0; r < 4; ++r) S[tau][r] = smp ? P.state_gdn[(((size_t)s * 8 + h) * 64 + 16 * tau + 4 * q4 + r) * 64 + e] : 0.f;
;     const float* GT = (const float*)(P.ws + WS_GT);
;     float* OA = (float*)((unsigned char*)P.out + YO_OA); float* OAS = (float*)(P.ws + WS_OAS);
; #pragma unroll 1
;     for (int n = 0; n < nsteps; ++n) {
;         const int cu = cu0 + n; const unsigned char* ops = P.ws + WS_OPS + ((size_t)cu * 8 + h) * OPS_UNIT;
;         const float gt = GT[cu * 8 + h];
;         const bf16x8* Wf = (const bf16x8*)(ops + OPS_W) + lane; const bf16x8* KT = (const bf16x8*)(ops + OPS_KT) + lane;
;         const bf16x8* QD = (const bf16x8*)(ops + OPS_QD) + lane; const bf16x8* QK = (const bf16x8*)(ops + OPS_QK) + lane;
;         const v2u* Up = (const v2u*)(ops + OPS_U) + (sl * 4) * 64 + lane;
;         bf16x8 Sb[2]; Sb[0] = pack8(S[0], S[1]); Sb[1] = pack8(S[2], S[3]);
;         f32x4 vn[4];
; #pragma unroll
;         for (int tau = 0; tau < 4; ++tau) { f32x4 av = {0.f, 0.f, 0.f, 0.f}; av = mfma16(Wf[(2 * tau) * 64], Sb[0], av); av = mfma16(Wf[(2 * tau + 1) * 64], Sb[1], av);
;             const v2u ub = Up[tau * 64]; const f32x4 u = {bflo(ub.x), bfhi(ub.x), bflo(ub.y), bfhi(ub.y)}; vn[tau] = u - av; }
.LBB0_639:
	v_readlane_b32 s18, v247, 0
	v_readlane_b32 s19, v247, 1
	s_add_u32 s29, s18, 0x1400000
	s_addc_u32 s30, s19, 0
	s_ashr_i32 s8, s96, 3
	s_lshl_b32 s0, s8, 7
	s_ashr_i32 s1, s0, 31
	s_and_b32 s2, s96, 7
	s_lshl_b64 s[14:15], s[0:1], 3
	s_add_u32 s10, s18, 0x3600000
	s_addc_u32 s11, s19, 0
	s_add_u32 s4, s18, 0xb700000
	s_addc_u32 s5, s19, 0
	s_ashr_i32 s9, s8, 31
	s_add_u32 s22, s18, 0x23900000
	s_addc_u32 s23, s19, 0
	s_or_b32 s12, s14, s2
	s_mul_i32 s13, s15, 0xa000
	s_mul_hi_u32 s16, s12, 0xa000
	s_add_i32 s16, s16, s13
	s_mul_i32 s12, s12, 0xa000
	s_add_u32 s12, s22, s12
	s_addc_u32 s13, s23, s16
	s_add_u32 s16, s18, 0x3d300000
	s_addc_u32 s17, s19, 0
	s_lshl_b32 s28, s96, 1
	s_ashr_i32 s18, s40, 8
	s_add_i32 s18, s18, s28
	s_ashr_i32 s26, s18, 3
	s_ashr_i32 s27, s26, 31
	s_and_b32 s34, s18, 7
	v_lshrrev_b32_e32 v1, 4, v164
	s_lshl_b64 s[18:19], s[26:27], 9
	v_and_b32_e32 v30, 15, v35
	v_lshl_or_b32 v2, v1, 2, s18
	s_bfe_u32 s24, s40, 0x20006
	v_lshl_or_b32 v2, s34, 6, v2
	v_mov_b32_e32 v3, s19
	v_lshlrev_b32_e32 v4, 2, v30
	v_mov_b32_e32 v165, 0
	v_lshl_or_b32 v4, s24, 6, v4
	v_mov_b32_e32 v5, v165
	v_lshlrev_b64 v[2:3], 8, v[2:3]
	v_lshl_add_u64 v[14:15], s[74:75], 0, v[4:5]
	v_or_b32_e32 v10, 0x1100, v2
	v_mov_b32_e32 v11, v3
	v_or_b32_e32 v8, 0x1000, v2
	v_mov_b32_e32 v9, v3
	v_lshl_add_u64 v[16:17], v[14:15], 0, v[10:11]
	v_or_b32_e32 v10, 0x1200, v2
	v_lshl_add_u64 v[6:7], v[14:15], 0, v[2:3]
	v_lshl_add_u64 v[8:9], v[14:15], 0, v[8:9]
	v_lshl_add_u64 v[18:19], v[14:15], 0, v[10:11]
	v_or_b32_e32 v10, 0x1300, v2
	s_add_i32 s18, s26, 0x400
	v_lshl_add_u64 v[20:21], v[14:15], 0, v[10:11]
	global_load_dword v10, v[6:7], off
	global_load_dword v11, v[6:7], off offset:256
	global_load_dword v12, v[6:7], off offset:512
	global_load_dword v13, v[6:7], off offset:768
	s_nop 0
	global_load_dword v6, v[8:9], off
	global_load_dword v7, v[16:17], off
	s_nop 0
	global_load_dword v8, v[18:19], off
	global_load_dword v9, v[20:21], off
	v_or_b32_e32 v18, 0x2100, v2
	v_mov_b32_e32 v19, v3
	s_ashr_i32 s19, s18, 31
	v_lshl_add_u64 v[22:23], v[14:15], 0, v[18:19]
	v_or_b32_e32 v18, 0x2200, v2
	s_lshl_b64 s[20:21], s[18:19], 3
	v_lshl_add_u64 v[28:29], v[14:15], 0, v[18:19]
	v_or_b32_e32 v18, 0x2300, v2
	s_or_b32 s19, s20, s34
	v_lshl_add_u64 v[32:33], v[14:15], 0, v[18:19]
	v_or_b32_e32 v18, 0x3000, v2
	s_mul_i32 s20, s21, 0xa000
	s_mul_hi_u32 s21, s19, 0xa000
	v_lshl_add_u64 v[36:37], v[14:15], 0, v[18:19]
	v_or_b32_e32 v18, 0x3100, v2
	s_add_i32 s21, s21, s20
	s_mul_i32 s19, s19, 0xa000
	v_or_b32_e32 v16, 0x2000, v2
	v_mov_b32_e32 v17, v3
	v_lshl_add_u64 v[38:39], v[14:15], 0, v[18:19]
	v_or_b32_e32 v18, 0x3200, v2
	s_add_u32 s20, s22, s19
	v_lshl_add_u64 v[16:17], v[14:15], 0, v[16:17]
	v_lshl_add_u64 v[40:41], v[14:15], 0, v[18:19]
	v_or_b32_e32 v2, 0x3300, v2
	s_addc_u32 s21, s23, s21
	v_lshlrev_b32_e32 v18, 4, v164
	v_lshl_add_u64 v[2:3], v[14:15], 0, v[2:3]
	global_load_dwordx4 v[24:27], v18, s[20:21]
	global_load_dword v20, v[16:17], off
	global_load_dword v21, v[22:23], off
	s_nop 0
	global_load_dword v22, v[28:29], off
	global_load_dword v23, v[32:33], off
	global_load_dword v14, v[36:37], off
	global_load_dword v15, v[38:39], off
	global_load_dword v16, v[40:41], off
	global_load_dword v17, v[2:3], off
	s_lshl_b32 s18, s18, 3
	global_load_dwordx4 v[36:39], v18, s[20:21] offset:1024
	global_load_dwordx4 v[40:43], v18, s[20:21] offset:2048
	s_or_b32 s18, s18, s34
	s_ashr_i32 s19, s18, 31
	s_lshl_b64 s[18:19], s[18:19], 2
	s_add_u32 s18, s29, s18
	s_addc_u32 s19, s30, s19
	s_lshl_b32 s22, s24, 11
	s_add_u32 s22, s20, s22
	s_addc_u32 s23, s21, 0
	v_lshlrev_b32_e32 v2, 3, v164
	v_mov_b32_e32 v3, v165
	v_lshl_add_u64 v[32:33], s[22:23], 0, v[2:3]
	s_mov_b32 s31, 0x8000
	v_mov_b32_e32 v19, v165
	v_add_co_u32_e32 v44, vcc, s31, v32
	s_movk_i32 s36, 0x2000
	v_lshl_add_u64 v[28:29], s[20:21], 0, v[18:19]
	v_addc_co_u32_e32 v45, vcc, 0, v33, vcc
	v_add_co_u32_e32 v82, vcc, s36, v28
	global_load_dwordx2 v[96:97], v[44:45], off
	s_nop 0
	global_load_dwordx4 v[44:47], v18, s[20:21] offset:3072
	v_addc_co_u32_e32 v83, vcc, 0, v29, vcc
	global_load_dwordx4 v[48:51], v[82:83], off offset:-4096
	s_movk_i32 s35, 0x1000
	v_add_co_u32_e32 v60, vcc, s35, v28
	s_mov_b64 s[24:25], 0x8000
	s_nop 0
	v_addc_co_u32_e32 v61, vcc, 0, v29, vcc
	global_load_dwordx4 v[52:55], v[60:61], off offset:1024
	v_lshl_add_u64 v[32:33], v[32:33], 0, s[24:25]
	global_load_dwordx2 v[98:99], v[32:33], off offset:512
	global_load_dwordx4 v[56:59], v[60:61], off offset:2048
	s_nop 0
	global_load_dwordx4 v[60:63], v[60:61], off offset:3072
	s_movk_i32 s22, 0x4000
	s_mov_b64 s[20:21], 0x4000
	v_add_co_u32_e32 v64, vcc, s22, v28
	v_lshl_add_u64 v[68:69], v[28:29], 0, s[20:21]
	s_nop 0
	v_addc_co_u32_e32 v65, vcc, 0, v29, vcc
	s_movk_i32 s20, 0x6000
	v_add_co_u32_e32 v72, vcc, s20, v28
	global_load_dwordx4 v[64:67], v[64:65], off
	s_nop 0
	v_addc_co_u32_e32 v73, vcc, 0, v29, vcc
	global_load_dwordx4 v[68:71], v[68:69], off offset:1024
	s_nop 0
	global_load_dwordx4 v[72:75], v[72:73], off
	s_nop 0
	global_load_dwordx2 v[100:101], v[32:33], off offset:1024
	s_nop 0
	global_load_dwordx2 v[32:33], v[32:33], off offset:1536
	s_nop 0
	global_load_dword v34, v165, s[18:19]
	s_waitcnt vmcnt(30)
	v_cvt_pk_bf16_f32 v76, v10, v11
	s_waitcnt vmcnt(28)
	v_cvt_pk_bf16_f32 v77, v12, v13
	s_waitcnt vmcnt(26)
	v_cvt_pk_bf16_f32 v78, v6, v7
	s_waitcnt vmcnt(24)
	v_cvt_pk_bf16_f32 v79, v8, v9
	s_mov_b64 s[18:19], 0x2000
	v_lshl_add_u64 v[92:93], v[28:29], 0, s[18:19]
	s_waitcnt vmcnt(23)
	v_mfma_f32_16x16x32_bf16 v[24:27], v[24:27], v[76:79], 0
	global_load_dwordx4 v[84:87], v[82:83], off
	global_load_dwordx4 v[88:91], v[92:93], off offset:1024
	s_waitcnt vmcnt(23)
; __device__ __forceinline__ float bflo(unsigned w) { return __uint_as_float(w << 16); }
; __device__ __forceinline__ float bfhi(unsigned w) { return __uint_as_float(w & 0xffff0000u); }
; __device__ __forceinline__ f32x4 mfma16(bf16x8 a, bf16x8 b, f32x4 c) { return __builtin_amdgcn_mfma_f32_16x16x32_bf16(a, b, c, 0, 0, 0); }
; __device__ __forceinline__ bf16x8 pack8(f32x4 a, f32x4 b) { v4u w; w.x = pk2(a[0], a[1]); w.y = pk2(a[2], a[3]); w.z = pk2(b[0], b[1]); w.w = pk2(b[2], b[3]); return __builtin_bit_cast(bf16x8, w); }
; __device__ __forceinline__ void scan_chain(const Params& P, bool smp, int s, int h, int sl, int lane) {
;     ...
;         bf16x8 Sb[2]; Sb[0] = pack8(S[0], S[1]); Sb[1] = pack8(S[2], S[3]);
;         f32x4 vn[4];
; #pragma unroll
;         for (int tau = 0; tau < 4; ++tau) { f32x4 av = {0.f, 0.f, 0.f, 0.f}; av = mfma16(Wf[(2 * tau) * 64], Sb[0], av); av = mfma16(Wf[(2 * tau + 1) * 64], Sb[1], av);
;             const v2u ub = Up[tau * 64]; const f32x4 u = {bflo(ub.x), bfhi(ub.x), bflo(ub.y), bfhi(ub.y)}; vn[tau] = u - av; }
;         bf16x8 Vb[2]; Vb[0] = pack8(vn[0], vn[1]); Vb[1] = pack8(vn[2], vn[3]);
;         f32x4 ao[4];
; #pragma unroll
;         for (int tau = 0; tau < 4; ++tau) { f32x4 a = {0.f, 0.f, 0.f, 0.f}; a = mfma16(QD[(2 * tau) * 64], Sb[0], a); a = mfma16(QD[(2 * tau + 1) * 64], Sb[1], a);
;             a = mfma16(QK[((tau < 2) ? tau : 2 * tau - 2) * 64], Vb[0], a); if (tau >= 2) a = mfma16(QK[(2 * tau - 1) * 64], Vb[1], a); ao[tau] = a; }
; #pragma unroll
;         for (int tau = 0; tau < 4; ++tau) { f32x4 a = S[tau] * gt; a = mfma16(KT[(2 * tau) * 64], Vb[0], a); a = mfma16(KT[(2 * tau + 1) * 64], Vb[1], a); S[tau] = a; }
;         if (!smp) { float* op = OA + ((size_t)s * TP + n * 64) * 512 + h * 64 + e;
; #pragma unroll
;             for (int tau = 0; tau < 4; ++tau)
; #pragma unroll
;                 for (int r = 0; r < 4; ++r) op[(size_t)(16 * tau + 4 * q4 + r) * 512] = ao[tau][r];
;         } else { float* op = OAS + ((size_t)s * 16) * 512 + h * 64 + e;
; #pragma unroll
;             for (int r = 0; r < 4; ++r) op[(size_t)(4 * q4 + r) * 512] = ao[0][r]; }
;     }
;     float* so = P.out + (smp ? O_GS : O_GP) + (((size_t)s * 8 + h) * 64) * 64 + e;
; #pragma unroll
;     for (int tau = 0; tau < 4; ++tau)
; #pragma unroll
;         for (int r = 0; r < 4; ++r) so[(size_t)(16 * tau + 4 * q4 + r) * 64] = S[tau][r];
	v_cvt_pk_bf16_f32 v80, v20, v21
	s_waitcnt vmcnt(21)
	v_cvt_pk_bf16_f32 v81, v22, v23
	s_waitcnt vmcnt(15)
	v_mfma_f32_16x16x32_bf16 v[40:43], v[40:43], v[76:79], 0
	v_cvt_pk_bf16_f32 v82, v14, v15
	v_cvt_pk_bf16_f32 v83, v16, v17
	s_movk_i32 s18, 0x3000
	v_readlane_b32 s72, v247, 7
	v_mfma_f32_16x16x32_bf16 v[24:27], v[36:39], v[80:83], v[24:27]
	global_load_dwordx4 v[36:39], v[92:93], off offset:2048
	v_readlane_b32 s82, v247, 17
	global_load_dwordx4 v[92:95], v[92:93], off offset:3072
	s_waitcnt vmcnt(15)
	v_mfma_f32_16x16x32_bf16 v[40:43], v[44:47], v[80:83], v[40:43]
	v_lshlrev_b32_e32 v19, 16, v96
	v_and_b32_e32 v31, 0xffff0000, v96
	s_nop 0
	v_sub_f32_e32 v31, v31, v25
	s_waitcnt vmcnt(14)
	v_mfma_f32_16x16x32_bf16 v[44:47], v[48:51], v[76:79], 0
	v_lshlrev_b32_e32 v48, 16, v97
	v_and_b32_e32 v49, 0xffff0000, v97
	v_sub_f32_e32 v96, v49, v27
	s_waitcnt vmcnt(13)
	v_mfma_f32_16x16x32_bf16 v[44:47], v[52:55], v[80:83], v[44:47]
	v_sub_f32_e32 v52, v48, v26
	v_sub_f32_e32 v19, v19, v24
	s_waitcnt vmcnt(12)
	v_lshlrev_b32_e32 v53, 16, v98
	s_waitcnt vmcnt(11)
	v_mfma_f32_16x16x32_bf16 v[24:27], v[56:59], v[76:79], 0
	v_and_b32_e32 v54, 0xffff0000, v98
	v_lshlrev_b32_e32 v48, 16, v99
	v_sub_f32_e32 v53, v53, v40
	s_waitcnt vmcnt(10)
	v_mfma_f32_16x16x32_bf16 v[24:27], v[60:63], v[80:83], v[24:27]
	v_cvt_pk_bf16_f32 v40, v19, v31
	v_sub_f32_e32 v55, v48, v42
	s_waitcnt vmcnt(6)
	v_lshlrev_b32_e32 v19, 16, v100
	v_and_b32_e32 v31, 0xffff0000, v100
	v_sub_f32_e32 v42, v54, v41
	v_sub_f32_e32 v31, v31, v45
	v_sub_f32_e32 v19, v19, v44
	v_cvt_pk_bf16_f32 v41, v52, v96
	v_cvt_pk_bf16_f32 v42, v53, v42
	v_lshlrev_b32_e32 v52, 16, v101
	v_and_b32_e32 v53, 0xffff0000, v101
	v_cvt_pk_bf16_f32 v44, v19, v31
	s_waitcnt vmcnt(5)
	v_lshlrev_b32_e32 v19, 16, v32
	v_and_b32_e32 v31, 0xffff0000, v32
	v_lshlrev_b32_e32 v32, 16, v33
	v_sub_f32_e32 v47, v53, v47
	v_sub_f32_e32 v46, v52, v46
	v_and_b32_e32 v33, 0xffff0000, v33
	v_sub_f32_e32 v52, v32, v26
	v_add_co_u32_e32 v32, vcc, s18, v28
	v_cvt_pk_bf16_f32 v45, v46, v47
	v_sub_f32_e32 v47, v33, v27
	v_addc_co_u32_e32 v33, vcc, 0, v29, vcc
	global_load_dwordx4 v[26:29], v[32:33], off offset:3072
	global_load_dwordx4 v[56:59], v[32:33], off offset:2048
	v_and_b32_e32 v49, 0xffff0000, v99
	v_sub_f32_e32 v43, v49, v43
	v_cvt_pk_bf16_f32 v43, v55, v43
	v_cvt_pk_bf16_f32 v47, v52, v47
	global_load_dwordx4 v[52:55], v[32:33], off
	s_waitcnt vmcnt(7)
	v_pk_mul_f32 v[8:9], v[8:9], v[34:35] op_sel_hi:[1,0]
	v_pk_mul_f32 v[6:7], v[6:7], v[34:35] op_sel_hi:[1,0]
	v_mfma_f32_16x16x32_bf16 v[48:51], v[64:67], v[76:79], 0
	s_lshl_b64 s[18:19], s[26:27], 15
	s_add_u32 s18, s16, s18
	v_pk_mul_f32 v[16:17], v[16:17], v[34:35] op_sel_hi:[1,0]
	s_waitcnt vmcnt(4)
	v_mfma_f32_16x16x32_bf16 v[6:9], v[36:39], v[40:43], v[6:9]
	global_load_dwordx4 v[36:39], v[32:33], off offset:1024
	v_pk_mul_f32 v[14:15], v[14:15], v[34:35] op_sel_hi:[1,0]
	s_addc_u32 s19, s17, s19
	v_mfma_f32_16x16x32_bf16 v[48:51], v[68:71], v[80:83], v[48:51]
	s_lshl_b32 s20, s34, 8
	s_add_u32 s18, s18, s20
	v_sub_f32_e32 v25, v31, v25
	s_waitcnt vmcnt(2)
	v_mfma_f32_16x16x32_bf16 v[14:17], v[56:59], v[40:43], v[14:17]
	v_sub_f32_e32 v19, v19, v24
	s_addc_u32 s19, s19, 0
	v_cvt_pk_bf16_f32 v46, v19, v25
	v_mfma_f32_16x16x32_bf16 v[48:51], v[72:75], v[40:43], v[48:51]
	v_lshl_add_u64 v[24:25], s[18:19], 0, v[4:5]
	s_lshl_b64 s[18:19], s[26:27], 17
	v_pk_mul_f32 v[12:13], v[12:13], v[34:35] op_sel_hi:[1,0]
	v_pk_mul_f32 v[10:11], v[10:11], v[34:35] op_sel_hi:[1,0]
	v_mfma_f32_16x16x32_bf16 v[14:17], v[26:29], v[44:47], v[14:17]
	v_lshlrev_b32_e32 v26, 13, v1
	v_mov_b32_e32 v27, v165
	s_add_u32 s18, s54, s18
	v_mfma_f32_16x16x32_bf16 v[10:13], v[84:87], v[40:43], v[10:13]
	v_lshl_add_u64 v[24:25], v[24:25], 0, v[26:27]
	s_addc_u32 s19, s55, s19
	s_lshl_b32 s20, s34, 14
	global_store_dword v[24:25], v48, off
	global_store_dword v[24:25], v49, off offset:2048
	v_add_co_u32_e32 v24, vcc, s35, v24
	s_add_u32 s18, s18, s20
	s_nop 0
	v_addc_co_u32_e32 v25, vcc, 0, v25, vcc
	s_addc_u32 s19, s19, 0
	v_pk_mul_f32 v[22:23], v[22:23], v[34:35] op_sel_hi:[1,0]
	v_pk_mul_f32 v[20:21], v[20:21], v[34:35] op_sel_hi:[1,0]
	global_store_dword v[24:25], v50, off
	global_store_dword v[24:25], v51, off offset:2048
	v_lshl_add_u64 v[4:5], s[18:19], 0, v[4:5]
	v_lshlrev_b32_e32 v24, 10, v1
	v_mov_b32_e32 v25, v165
	v_mfma_f32_16x16x32_bf16 v[10:13], v[88:91], v[44:47], v[10:13]
	v_lshl_add_u64 v[4:5], v[4:5], 0, v[24:25]
	s_mov_b64 s[18:19], 0x1126c000
	v_lshl_add_u64 v[24:25], v[4:5], 0, s[18:19]
	s_waitcnt vmcnt(5)
	v_mfma_f32_16x16x32_bf16 v[20:23], v[52:55], v[40:43], v[20:23]
	s_mov_b32 s18, 0x1126d000
	v_add_co_u32_e32 v26, vcc, s18, v4
	v_mfma_f32_16x16x32_bf16 v[6:9], v[92:95], v[44:47], v[6:9]
	s_nop 0
	v_addc_co_u32_e32 v27, vcc, 0, v5, vcc
	s_mov_b32 s18, 0x1126e000
	s_waitcnt vmcnt(4)
	v_mfma_f32_16x16x32_bf16 v[20:23], v[36:39], v[44:47], v[20:23]
	global_store_dword v[26:27], v10, off offset:-4096
	global_store_dword v[24:25], v11, off offset:256
	global_store_dword v[24:25], v12, off offset:512
	global_store_dword v[24:25], v13, off offset:768
	global_store_dword v[26:27], v6, off
	global_store_dword v[26:27], v7, off offset:256
	global_store_dword v[26:27], v8, off offset:512
	global_store_dword v[26:27], v9, off offset:768
	v_add_co_u32_e32 v6, vcc, s18, v4
	s_mov_b32 s18, 0x1126f000
	s_nop 0
	v_addc_co_u32_e32 v7, vcc, 0, v5, vcc
	v_add_co_u32_e32 v4, vcc, s18, v4
	v_ashrrev_i32_e32 v1, 8, v35
	s_nop 0
	v_addc_co_u32_e32 v5, vcc, 0, v5, vcc
	v_add_u32_e32 v1, s28, v1
	global_store_dword v[4:5], v20, off offset:-4096
	global_store_dword v[6:7], v21, off offset:256
	global_store_dword v[6:7], v22, off offset:512
	global_store_dword v[6:7], v23, off offset:768
	global_store_dword v[4:5], v14, off
	global_store_dword v[4:5], v15, off offset:256
	global_store_dword v[4:5], v16, off offset:512
	global_store_dword v[4:5], v17, off offset:768
	v_ashrrev_i32_e32 v4, 3, v1
	v_ashrrev_i32_e32 v5, 31, v4
	v_lshrrev_b32_e32 v6, 4, v35
	v_lshlrev_b64 v[8:9], 4, v[4:5]
	v_and_or_b32 v8, v6, 15, v8
	v_lshlrev_b32_e32 v1, 6, v1
	v_lshlrev_b64 v[4:5], 11, v[8:9]
	v_and_b32_e32 v1, 0x1c0, v1
	v_lshl_add_u64 v[4:5], s[16:17], 0, v[4:5]
	v_lshlrev_b32_e32 v6, 2, v1
	v_mov_b32_e32 v7, v165
	v_lshl_add_u64 v[4:5], v[4:5], 0, v[6:7]
	v_lshlrev_b32_e32 v6, 2, v35
	v_and_b32_e32 v12, 60, v6
	v_lshlrev_b32_e32 v10, 2, v12
	v_mov_b32_e32 v11, v165
	v_lshl_add_u64 v[4:5], v[4:5], 0, v[10:11]
	s_waitcnt vmcnt(0)
	s_barrier
; __device__ __forceinline__ unsigned pk2(float lo, float hi) { return pg8::cvt_pk_bf16_v(lo, hi); }
; __device__ __forceinline__ float bflo(unsigned w) { return __uint_as_float(w << 16); }
; __device__ __forceinline__ float bfhi(unsigned w) { return __uint_as_float(w & 0xffff0000u); }
; __device__ __forceinline__ float siluf(float x) { return x * __builtin_amdgcn_rcpf(1.0f + __expf(-x)); }
; __device__ __forceinline__ void scan_prompt_wg(const Params& P, LAS unsigned char* lds, int s, int h, int wave, int lane) {
;     ...
;         const int sl = wave, l15 = lane & 15, q4 = lane >> 4, e = 16 * sl + l15;
;         f32x4 S[4];
; #pragma unroll
;         for (int tau = 0; tau < 4; ++tau) S[tau] = (f32x4){0.f, 0.f, 0.f, 0.f};
;         const float* GT = (const float*)(P.ws + WS_GT) + (size_t)(s * 128) * 8 + h;
;         const v2u* Ug = (const v2u*)(ops0 + OPS_U) + (sl * 4) * 64 + lane;
;         v2u ua[4], ub[4];
; #pragma unroll
;         for (int tau = 0; tau < 4; ++tau) { ua[tau] = Ug[tau * 64]; ub[tau] = (Ug + step_stride / 8)[tau * 64]; }
;         SCAN_BAR();
;         int slot = 0;
;         float gt = GT[0];
; __global__ void __launch_bounds__(NWAVES * 64, 2) fwd_kernel(Params P) {
;     ...
;                 const int pr = (int)blockIdx.x * 2 + (tid >> 8), sp = pr >> 3, hp_ = pr & 7, t = (tid >> 4) & 15, part = tid & 15;
;                 const size_t row = (size_t)sp * 16 + t;
;                 const f32x4 o4 = *(const f32x4*)((const float*)(ws + WS_OAS) + row * 512 + hp_ * 64 + 4 * part);
;                 float ss = (o4[0] * o4[0] + o4[1] * o4[1]) + (o4[2] * o4[2] + o4[3] * o4[3]);
;                 ss += __shfl_xor(ss, 1); ss += __shfl_xor(ss, 2); ss += __shfl_xor(ss, 4); ss += __shfl_xor(ss, 8);
;                 const float rstd = __builtin_amdgcn_rsqf(ss * (1.0f / 64.0f) + 1e-6f);
;                 const size_t mo = ((size_t)MP + row) * 1024 + hp_ * 64 + 4 * part;
;                 const v2u zb = *(const v2u*)((const bf16*)(ws + WS_Z) + mo);
;                 const f32x4 g4 = *(const f32x4*)(P.gdn_g + 4 * part);
;                 v2u o; o.x = pk2(o4[0] * rstd * g4[0] * siluf(bflo(zb.x)), o4[1] * rstd * g4[1] * siluf(bfhi(zb.x))); o.y = pk2(o4[2] * rstd * g4[2] * siluf(bflo(zb.y)), o4[3] * rstd * g4[3] * siluf(bfhi(zb.y)));
;                 *(v2u*)((bf16*)(ws + WS_MIX) + mo) = o;
	global_load_dwordx4 v[4:7], v[4:5], off
	v_lshlrev_b64 v[8:9], 10, v[8:9]
	v_or3_b32 v8, v8, v1, v12
	v_mov_b64_e32 v[12:13], 0x8000000
	v_lshl_add_u64 v[12:13], v[8:9], 1, v[12:13]
	v_lshl_add_u64 v[8:9], s[10:11], 0, v[12:13]
	global_load_dwordx2 v[14:15], v[8:9], off
	v_readlane_b32 s83, v247, 18
	v_mbcnt_lo_u32_b32 v1, -1, 0
	v_mbcnt_hi_u32_b32 v1, -1, v1
	v_xor_b32_e32 v53, 1, v1
	v_xor_b32_e32 v54, 2, v1
	v_xor_b32_e32 v55, 4, v1
	global_load_dwordx4 v[8:11], v10, s[82:83]
	v_xor_b32_e32 v56, 8, v1
	v_mov_b32_e32 v19, 0x358637bd
	s_mov_b64 s[46:47], s[82:83]
	s_mov_b64 s[16:17], -1
	s_cmp_lt_i32 s33, 4
	s_mul_hi_i32 s26, s0, 0x50000
	s_mul_i32 s27, s0, 0x50000
	s_mul_i32 s28, s2, 0xa000
	v_readlane_b32 s73, v247, 8
	v_readlane_b32 s74, v247, 9
	v_readlane_b32 s75, v247, 10
	v_readlane_b32 s76, v247, 11
	v_readlane_b32 s77, v247, 12
	v_readlane_b32 s78, v247, 13
	v_readlane_b32 s79, v247, 14
	v_readlane_b32 s80, v247, 15
	v_readlane_b32 s81, v247, 16
	v_readlane_b32 s84, v247, 19
	v_readlane_b32 s85, v247, 20
	v_readlane_b32 s86, v247, 21
	v_readlane_b32 s87, v247, 22
	s_waitcnt vmcnt(2)
	v_pk_mul_f32 v[16:17], v[6:7], v[6:7]
	v_pk_mul_f32 v[20:21], v[4:5], v[4:5]
	s_nop 0
	v_pk_mov_b32 v[22:23], v[20:21], v[16:17] op_sel:[1,0]
	v_mov_b32_e32 v21, v17
	v_pk_add_f32 v[16:17], v[22:23], v[20:21]
	s_nop 0
	v_add_f32_e32 v16, v16, v17
	v_and_b32_e32 v17, 64, v1
	v_add_u32_e32 v52, 64, v17
	v_cmp_lt_i32_e32 vcc, v53, v52
	s_nop 1
	v_cndmask_b32_e32 v17, v1, v53, vcc
	v_lshlrev_b32_e32 v57, 2, v17
	ds_bpermute_b32 v17, v57, v16
	v_cmp_lt_i32_e32 vcc, v54, v52
	s_waitcnt lgkmcnt(0)
	v_add_f32_e32 v16, v16, v17
	v_cndmask_b32_e32 v17, v1, v54, vcc
	v_lshlrev_b32_e32 v58, 2, v17
	ds_bpermute_b32 v17, v58, v16
	v_cmp_lt_i32_e32 vcc, v55, v52
	s_waitcnt lgkmcnt(0)
	v_add_f32_e32 v16, v16, v17
	v_cndmask_b32_e32 v17, v1, v55, vcc
	v_lshlrev_b32_e32 v17, 2, v17
	ds_bpermute_b32 v17, v17, v16
	v_cmp_lt_i32_e32 vcc, v56, v52
	s_waitcnt lgkmcnt(0)
	v_add_f32_e32 v16, v16, v17
	v_cndmask_b32_e32 v17, v1, v56, vcc
	v_lshlrev_b32_e32 v17, 2, v17
	ds_bpermute_b32 v17, v17, v16
	s_waitcnt lgkmcnt(0)
	v_add_f32_e32 v16, v16, v17
	v_fmac_f32_e32 v19, 0x3c800000, v16
	s_waitcnt vmcnt(1)
	v_lshlrev_b32_e32 v16, 16, v14
	v_and_b32_e32 v17, 0xffff0000, v14
	v_mul_f32_e32 v14, 0xbfb8aa3b, v16
	v_exp_f32_e32 v20, v14
	v_mul_f32_e32 v14, 0xbfb8aa3b, v17
	v_exp_f32_e32 v21, v14
	v_rsq_f32_e32 v14, v19
	v_add_f32_e32 v19, 1.0, v20
	v_rcp_f32_e32 v20, v19
	v_add_f32_e32 v19, 1.0, v21
	v_rcp_f32_e32 v21, v19
	v_pk_mul_f32 v[4:5], v[4:5], v[14:15] op_sel_hi:[1,0]
	s_waitcnt vmcnt(0)
	v_pk_mul_f32 v[4:5], v[8:9], v[4:5]
	v_pk_mul_f32 v[8:9], v[20:21], v[16:17]
	v_lshlrev_b32_e32 v16, 16, v15
	v_and_b32_e32 v17, 0xffff0000, v15
	v_mul_f32_e32 v15, 0xbfb8aa3b, v16
	v_mul_f32_e32 v19, 0xbfb8aa3b, v17
	v_exp_f32_e32 v15, v15
	v_exp_f32_e32 v19, v19
	v_pk_mul_f32 v[4:5], v[4:5], v[8:9]
	v_add_f32_e32 v8, 1.0, v15
	v_add_f32_e32 v9, 1.0, v19
	v_rcp_f32_e32 v8, v8
	v_rcp_f32_e32 v9, v9
	v_pk_mul_f32 v[6:7], v[6:7], v[14:15] op_sel_hi:[1,0]
	v_cvt_pk_bf16_f32 v4, v4, v5
	v_pk_mul_f32 v[6:7], v[10:11], v[6:7]
	v_pk_mul_f32 v[8:9], v[8:9], v[16:17]
	s_nop 0
	v_pk_mul_f32 v[6:7], v[6:7], v[8:9]
	s_nop 0
	v_cvt_pk_bf16_f32 v5, v6, v7
	v_lshl_add_u64 v[6:7], s[4:5], 0, v[12:13]
	global_store_dwordx2 v[6:7], v[4:5], off
	s_barrier
	s_cbranch_scc0 .LBB0_654
	s_lshl_b32 s16, s33, 8
	s_ashr_i32 s17, s16, 31
	s_lshl_b64 s[16:17], s[16:17], 3
	s_add_u32 s18, s12, s16
	s_addc_u32 s19, s13, s17
	v_lshl_add_u64 v[4:5], s[18:19], 0, v[2:3]
	v_add_co_u32_e32 v8, vcc, s31, v4
	s_mov_b32 s19, 0x58000
	s_nop 0
	v_addc_co_u32_e32 v9, vcc, 0, v5, vcc
	v_lshl_add_u64 v[6:7], v[4:5], 0, s[24:25]
	v_add_co_u32_e32 v4, vcc, s19, v4
	s_lshl_b64 s[14:15], s[14:15], 2
	s_nop 0
	v_addc_co_u32_e32 v5, vcc, 0, v5, vcc
	global_load_dwordx2 v[50:51], v[8:9], off nt
	global_load_dwordx2 v[48:49], v[6:7], off offset:512 nt
	global_load_dwordx2 v[46:47], v[6:7], off offset:1024 nt
	global_load_dwordx2 v[44:45], v[6:7], off offset:1536 nt
	global_load_dwordx2 v[22:23], v[4:5], off nt
	global_load_dwordx2 v[24:25], v[4:5], off offset:512 nt
	global_load_dwordx2 v[26:27], v[4:5], off offset:1024 nt
	global_load_dwordx2 v[28:29], v[4:5], off offset:1536 nt
	s_add_u32 s14, s29, s14
	s_addc_u32 s15, s30, s15
	s_lshl_b32 s18, s2, 2
	s_barrier
	v_mov_b32_e32 v4, s18
	global_load_dword v34, v4, s[14:15]
	s_lshl_b64 s[0:1], s[0:1], 5
	s_or_b32 s0, s0, s18
	v_readlane_b32 s18, v247, 0
	v_readlane_b32 s19, v247, 1
	s_add_u32 s0, s18, s0
	s_addc_u32 s1, s19, s1
	s_add_u32 s14, s0, 0x1400020
	s_addc_u32 s15, s1, 0
	s_add_u32 s0, s27, s28
	s_addc_u32 s1, s26, 0
	s_add_u32 s0, s0, s16
	s_addc_u32 s1, s1, s17
	v_lshrrev_b32_e32 v4, 2, v164
	s_add_u32 s0, s18, s0
	v_and_b32_e32 v73, 12, v4
	s_addc_u32 s1, s19, s1
	v_lshl_or_b32 v20, s33, 4, v30
	v_or_b32_e32 v72, 1, v73
	v_or_b32_e32 v71, 2, v73
	v_or_b32_e32 v70, 3, v4
	v_or_b32_e32 v69, 16, v73
	v_or_b32_e32 v68, 17, v73
	v_or_b32_e32 v67, 18, v73
	v_or_b32_e32 v66, 19, v4
	v_or_b32_e32 v65, 32, v73
	v_or_b32_e32 v64, 33, v73
	v_or_b32_e32 v63, 34, v73
	v_or_b32_e32 v62, 35, v4
	v_or_b32_e32 v61, 48, v73
	v_or_b32_e32 v60, 49, v73
	v_or_b32_e32 v59, 50, v73
	v_or_b32_e32 v19, 51, v4
	v_lshl_add_u64 v[2:3], s[0:1], 0, v[2:3]
	s_mov_b64 s[0:1], 0x239a8400
	s_mov_b32 s31, 0
	v_lshrrev_b32_e32 v21, 2, v73
	v_xor_b32_e32 v21, s33, v21
	v_lshl_or_b32 v21, v21, 4, v30
	v_lshlrev_b32_e32 v21, 1, v21
	v_lshlrev_b32_e32 v74, 7, v73
	v_lshlrev_b32_e32 v75, 7, v72
	v_lshlrev_b32_e32 v76, 7, v71
	v_lshlrev_b32_e32 v77, 7, v70
	v_lshlrev_b32_e32 v78, 7, v69
	v_lshlrev_b32_e32 v79, 7, v68
	v_lshlrev_b32_e32 v80, 7, v67
	v_lshlrev_b32_e32 v81, 7, v66
	v_lshlrev_b32_e32 v82, 7, v65
	v_lshlrev_b32_e32 v83, 7, v64
	v_lshlrev_b32_e32 v84, 7, v63
	v_lshlrev_b32_e32 v85, 7, v62
	v_lshlrev_b32_e32 v86, 7, v61
	v_lshlrev_b32_e32 v87, 7, v60
	v_lshlrev_b32_e32 v88, 7, v59
	v_lshlrev_b32_e32 v89, 7, v19
	v_lshl_add_u32 v90, v164, 4, 0
	v_lshl_add_u64 v[30:31], v[2:3], 0, s[0:1]
	s_mov_b32 s29, 0x1e000
	s_mov_b64 s[16:17], 0x50000
	v_mov_b32_e32 v32, 0
	s_mov_b32 s30, 0
	v_mov_b32_e32 v14, v165
	v_mov_b32_e32 v15, v165
	v_mov_b32_e32 v16, v165
	v_mov_b32_e32 v17, v165
	v_mov_b32_e32 v10, v165
	v_mov_b32_e32 v11, v165
	v_mov_b32_e32 v12, v165
	v_mov_b32_e32 v13, v165
	v_mov_b32_e32 v2, v165
	v_mov_b32_e32 v3, v165
	v_mov_b32_e32 v4, v165
	v_mov_b32_e32 v5, v165
	v_mov_b32_e32 v6, v165
	v_mov_b32_e32 v7, v165
	v_mov_b32_e32 v8, v165
	v_mov_b32_e32 v9, v165
	s_branch .LBB0_643

; #define LAS __attribute__((address_space(3)))
; __device__ __forceinline__ void unpack8(v4u w, float (&f)[8]) { f[0] = bflo(w.x); f[1] = bfhi(w.x); f[2] = bflo(w.y); f[3] = bfhi(w.y); f[4] = bflo(w.z); f[5] = bfhi(w.z); f[6] = bflo(w.w); f[7] = bfhi(w.w); }
; #define SCAN_BAR() do { asm volatile("" ::: "memory"); __builtin_amdgcn_s_barrier(); asm volatile("" ::: "memory"); } while (0)
; #define SCAN_ISSUE(n, slot) do { const unsigned char* s_ = src + (size_t)(n) * step_stride; LAS unsigned char* d_ = lds + (slot) * SR_SLOT + p0 * 1024; \
;         _Pragma("unroll") for (int i_ = 0; i_ < 7; ++i_) glds16_asm(s_ + i_ * 1024, d_ + i_ * 1024, true  ); \
;         if (lw < 2) glds16_asm(s_ + 7 * 1024, d_ + 7 * 1024, true); } while (0)
; #define SCAN_ZISSUE(n) do { const unsigned char* z_ = zsrc + (size_t)(n) * 64 * 2048; LAS unsigned char* d_ = lds + ZT_OFF + ((n) & 1) * 8192 + (2 * lw) * 1024; \
;         glds16_asm(z_, d_, false); glds16_asm(z_ + 8 * 2048, d_ + 1024, false); } while (0)
; __device__ __forceinline__ void scan_prompt_wg(const Params& P, LAS unsigned char* lds, int s, int h, int wave, int lane) {
;     ...
;         const int ftid = lw * 64 + lane, ft = ftid >> 2, fp = ftid & 3;
;         float gg[16];
; #pragma unroll
;         for (int i = 0; i < 16; ++i) gg[i] = P.gdn_g[16 * fp + i];
;         bf16* Mr = (bf16*)(P.ws + WS_MIX) + ((size_t)s * TP + ft) * 1024 + h * 64 + 16 * fp;
;         const unsigned char* zsrc = (const unsigned char*)((const bf16*)(P.ws + WS_Z) + ((size_t)s * TP + 16 * lw + (lane >> 3)) * 1024 + h * 64) + (lane & 7) * 16;
;     ...
; #pragma unroll
;         for (int i = 0; i < 16; ++i) asm volatile("" : "+v"(gg[i]));
;         SCAN_ZISSUE(0);
;         SCAN_ISSUE(0, 0); SCAN_ISSUE(1, 1); SCAN_ISSUE(2, 2);
;         if (lw < 2) asm volatile("s_waitcnt vmcnt(16)" ::: "memory"); else asm volatile("s_waitcnt vmcnt(14)" ::: "memory");
;         SCAN_BAR();
;         int slot = 3;
; #pragma unroll 1
;         for (int n = 0; n <= NST; ++n) {
;             if (n >= 1) {
;                 const LAS unsigned char* ot = lds + (((n - 1) & 1) ? OT_B : OT_A) + ft * 128 + fp * 32;
;                 const LAS unsigned char* zt = lds + ZT_OFF + ((n - 1) & 1) * 8192 + ft * 128 + fp * 32;
;                 float o[16], zf[16]; { float t0[8], t1[8]; unpack8(*(const LAS v4u*)ot, t0); unpack8(*(const LAS v4u*)(ot + 16), t1);
.LBB0_663:
	v_lshl_or_b32 v15, s17, 6, v164
	s_lshl_b32 s10, s18, 1
	v_lshrrev_b32_e32 v26, 2, v15
	v_mov_b32_e32 v27, 0
	s_add_u32 s4, s4, s10
	v_lshl_add_u64 v[30:31], s[14:15], 0, v[26:27]
	s_addc_u32 s5, s5, 0
	v_lshlrev_b64 v[30:31], 11, v[30:31]
	v_lshl_add_u64 v[30:31], s[4:5], 0, v[30:31]
	v_mov_b32_e32 v15, v27
	v_lshlrev_b32_e32 v23, 7, v26
	v_lshlrev_b32_e32 v27, 5, v28
	s_add_i32 s4, 0, 0x22200
	v_bfe_u32 v100, v26, 2, 2
	v_xor_b32_e32 v100, v100, v28
	v_lshl_add_u32 v26, v100, 5, v23
	v_add3_u32 v27, s4, v23, v27
	s_add_u32 s4, s27, s28
	s_addc_u32 s5, s26, 0
	s_add_u32 s4, s4, s12
	s_addc_u32 s5, s5, s13
	v_readlane_b32 s12, v247, 0
	v_readlane_b32 s13, v247, 1
	s_add_u32 s4, s12, s4
	s_addc_u32 s5, s13, s5
	v_lshl_add_u64 v[18:19], s[4:5], 0, v[18:19]
	s_mov_b64 s[4:5], 0x23900000
	v_lshl_add_u64 v[18:19], v[18:19], 0, s[4:5]
	s_add_u32 s4, s16, s14
	s_addc_u32 s5, s15, 0
	v_lshl_add_u64 v[24:25], s[4:5], 0, v[24:25]
	v_lshlrev_b64 v[24:25], 11, v[24:25]
	v_lshl_or_b32 v23, s2, 7, v24
	s_barrier
	v_or_b32_e32 v24, v23, v22
	v_lshlrev_b32_e32 v14, 1, v14
	v_lshl_add_u64 v[22:23], s[12:13], 0, v[24:25]
	s_mov_b64 s[4:5], 0x3620000
	s_mov_b32 s11, 0
	v_lshl_add_u64 v[14:15], v[30:31], 0, v[14:15]
	v_lshl_add_u64 v[22:23], v[22:23], 0, s[4:5]
	s_mov_b32 s2, 3
	s_movk_i32 s43, 0x2000
	s_mov_b32 s10, -1
	s_mov_b32 s44, 0x1e000
	v_mov_b32_e32 v24, 0x358637bd
	s_mov_b64 s[4:5], 0x4000
	s_mov_b64 s[12:13], 0xf0000
	s_mov_b64 s[14:15], 0xf0400
	s_mov_b64 s[16:17], 0xf0800
	s_mov_b64 s[18:19], 0xf0c00
	s_mov_b64 s[24:25], 0xf1000
	s_mov_b64 s[26:27], 0xf1400
	s_mov_b64 s[28:29], 0xf1800
	s_mov_b64 s[30:31], 0xf1c00
	s_mov_b64 s[34:35], 0x50000
	s_mov_b64 s[36:37], 0x20000
	s_branch .LBB0_666
